# loop-head alignment: the back-edge targets of the MLA and FoX tile loops aligned to 64 bytes (.p2align 6 in the unreachable gap in front of them)
# baseline (speedup 1.0000x reference)
;     ...
;     bf16x8 qf[KS];
; #pragma unroll
;     for (int ks = 0; ks < KS; ++ks) {
;         if (ks < 4) qf[ks] = *(const bf16x8*)(qa + (size_t)myq * ldqa + ks * 16 + h * 8);
;         else qf[ks] = *(const bf16x8*)(qb + (size_t)myq * ldqb + (ks - 4) * 16 + h * 8);
;     }
; DI void phase3(const Params& p, unsigned char* smem, int tid, int cidx) {
;     ...
;         for (int r = 0; r < 2; ++r) {
;             const int bh = (r * 4 + s4) * 8 + xcd, b = bh >> 4, hd = bh & 15;
;             const size_t t0 = (size_t)b * L;
;             for (int half = 0; half < 2; ++half) {
;                 const int qi = half == 0 ? 15 - j8 : j8;
;                 bf16_t* qn = (bf16_t*)(ws + OFF_QN) + t0 * 1024 + hd * 64;
;                 attn_unit<96, false>(qn, 1024, (const bf16_t*)(ws + OFF_QPE) + t0 * 512 + hd * 32, 512,
;                                      (const bf16_t*)(ob + OUT_KM) + t0 * 1536 + hd * 96, 1536,
;                                      (const bf16_t*)(ws + OFF_VMT) + (size_t)(b * NH + hd) * 64 * LP, nullptr, qn, 1024, qi, lds, tid);
.Lmp_last_r:
	s_and_b64 vcc, exec, s[46:47]
	s_cbranch_vccnz .LBB0_747
	s_lshl_b64 s[98:99], s[100:101], 11
	s_add_u32 s98, s17, s98
	s_addc_u32 s99, s33, s99
	v_lshlrev_b32_e32 v44, 1, v152
	v_mov_b32_e32 v45, 0
	v_lshl_add_u64 v[44:45], s[98:99], 0, v[44:45]
	v_add3_u32 v40, v137, s59, 16
	v_add_u32_e32 v40, v40, v208
	v_ashrrev_i32_e32 v41, 31, v40
	v_lshlrev_b64 v[42:43], 10, v[40:41]
	v_lshlrev_b64 v[40:41], 11, v[40:41]
	v_lshl_add_u64 v[40:41], v[44:45], 0, v[40:41]
	global_load_dwordx4 v[66:69], v[40:41], off
	global_load_dwordx4 v[70:73], v[40:41], off offset:32
	global_load_dwordx4 v[74:77], v[40:41], off offset:64
	global_load_dwordx4 v[78:81], v[40:41], off offset:96
	s_lshl_b64 s[98:99], s[100:101], 10
	v_lshl_add_u64 v[44:45], v[148:149], 0, s[98:99]
	v_lshl_add_u64 v[42:43], v[44:45], 0, v[42:43]
	global_load_dwordx4 v[82:85], v[42:43], off
	global_load_dwordx4 v[86:89], v[42:43], off offset:32
	s_branch .LBB0_747
	.p2align	6

; DI float bf_lo(unsigned u) { return __uint_as_float(u << 16); }
; DI float bf_hi(unsigned u) { return __uint_as_float(u & 0xffff0000u); }
;     ...
;     if (FOX) {
;         float q2 = 0.f;
; #pragma unroll
;         for (int ks = 0; ks < 4; ++ks) {
;             const u32x4 w = __builtin_bit_cast(u32x4, qf[ks]);
; #pragma unroll
;             for (int e = 0; e < 4; ++e) { const float a = bf_lo(w[e]), b2 = bf_hi(w[e]); q2 += a * a + b2 * b2; }
;         }
;         { const auto sw = __builtin_amdgcn_permlane32_swap(__float_as_uint(q2), __float_as_uint(q2), false, false);
;           q2 = __uint_as_float(sw[0]) + __uint_as_float(sw[1]); }
;         qkb = sqrtf(q2 * kmax2) * 1.01f + 0.01f;
;     }
;     constexpr int NK2 = (64 * KCH + NT - 1) / NT;
;     u32x4 kr[NK2]; u32x4 vr; float br = 0.f;
;     auto gload = [&](int j) {
; #pragma unroll
;         for (int r = 0; r < NK2; ++r) {
;             const int c = tid + NT * r;
;             if (c < 64 * KCH) { const int row = c / KCH, ch = c - row * KCH; kr[r] = *(const u32x4*)(kbase + (size_t)(64 * j + row) * ldk + ch * 8); }
;         }
;         { const int row = tid >> 3, ch = tid & 7; vr = *(const u32x4*)(vt + (size_t)row * LP + 64 * j + ch * 8); }
;         if (FOX) { if (tid < 64) br = bias[64 * j + tid]; }
;     };
;     auto lstore = [&](int st) {
;         unsigned char* base = lds + st * STG;
; #pragma unroll
;         for (int r = 0; r < NK2; ++r) {
;             const int c = tid + NT * r;
;             if (c < 64 * KCH) { const int row = c / KCH, ch = c - row * KCH; *(u32x4*)(base + row * KROW + ch * 16) = kr[r]; }
;         }
;         { const int row = tid >> 3, ch = tid & 7; unsigned char* d = base + KBYTES + row * VROW + ch * 16;
;           *(u32x2*)d = (u32x2){vr[0], vr[1]}; *(u32x2*)(d + 8) = (u32x2){vr[2], vr[3]}; }
;         if (FOX) { if (tid < 64) *(float*)(base + KBYTES + VBYTES + tid * 4) = br; }
;     };
;     const int jlast = nkt - 1;
;     gload(jlast); lstore(0);
;     __syncthreads();
;     m = -1e30f;
.LBB0_787:
	s_or_b64 exec, exec, s[18:19]
	v_add3_u32 v6, v170, v191, s87
	s_waitcnt vmcnt(0)
	ds_write2_b64 v6, v[100:101], v[102:103] offset1:1
	s_and_saveexec_b64 s[18:19], s[8:9]
	v_add_u32_e32 v6, 0, v171
	ds_write_b32 v6, v130 offset:19968
	s_or_b64 exec, exec, s[18:19]
	s_cmp_gt_i32 s93, 16
	s_waitcnt lgkmcnt(0)
	s_barrier
	s_cbranch_scc1 .LBB0_820
	v_add_f32_e32 v4, v4, v5
	v_mul_f32_e32 v1, v1, v4
	s_mov_b32 s2, 0xf800000
	v_mul_f32_e32 v4, 0x4f800000, v1
	v_cmp_gt_f32_e32 vcc, s2, v1
	v_lshl_add_u64 v[124:125], v[140:141], 1, v[2:3]
	s_ashr_i32 s71, s22, 6
	v_cndmask_b32_e32 v1, v1, v4, vcc
	v_sqrt_f32_e32 v4, v1
	v_mov_b32_e32 v14, v0
	v_mov_b32_e32 v15, v0
	v_mov_b32_e32 v5, v0
	v_add_u32_e32 v2, -1, v4
	v_fma_f32 v3, -v2, v4, v1
	v_cmp_ge_f32_e64 s[18:19], 0, v3
	v_add_u32_e32 v3, 1, v4
	v_mov_b32_e32 v6, v0
	v_cndmask_b32_e64 v2, v4, v2, s[18:19]
	v_fma_f32 v4, -v3, v4, v1
	v_cmp_lt_f32_e64 s[18:19], 0, v4
	v_mov_b32_e32 v4, v0
	v_mov_b32_e32 v7, v0
	v_cndmask_b32_e64 v2, v2, v3, s[18:19]
	v_mul_f32_e32 v3, 0x37800000, v2
	v_cndmask_b32_e32 v2, v2, v3, vcc
	v_cmp_class_f32_e32 vcc, v1, v204
	s_max_i32 s18, s71, 0
	s_lshl_b32 s60, s18, 6
	v_cndmask_b32_e32 v1, v2, v1, vcc
	v_fmamk_f32 v156, v1, 0x3f8147ae, v205
	v_subrev_u32_e32 v1, s70, v178
	s_lshl_b32 s18, s93, 8
	v_subrev_u32_e32 v135, s18, v1
	v_mov_b32_e32 v1, v0
	v_mov_b32_e32 v2, v0
	v_mov_b32_e32 v3, v0
	v_mov_b32_e32 v8, v0
	v_mov_b32_e32 v9, v0
	v_mov_b32_e32 v10, v0
	v_mov_b32_e32 v11, v0
	v_mov_b32_e32 v12, v0
	v_mov_b32_e32 v13, v0
	v_mov_b64_e32 v[46:47], v[14:15]
	v_mov_b64_e32 v[30:31], v[14:15]
	s_mov_b32 s2, 0
	v_lshl_add_u64 v[126:127], v[150:151], 1, s[20:21]
	v_add_u32_e32 v131, 31, v209
	v_add_u32_e32 v133, s70, v176
	v_add_u32_e32 v134, s70, v177
	s_mov_b64 s[74:75], 0
	v_mov_b32_e32 v132, 0
	v_mov_b32_e32 v129, 0xf149f2ca
	v_mov_b64_e32 v[44:45], v[12:13]
	v_mov_b64_e32 v[42:43], v[10:11]
	v_mov_b64_e32 v[40:41], v[8:9]
	v_mov_b64_e32 v[38:39], v[6:7]
	v_mov_b64_e32 v[36:37], v[4:5]
	v_mov_b64_e32 v[34:35], v[2:3]
	v_mov_b64_e32 v[32:33], v[0:1]
	v_mov_b64_e32 v[28:29], v[12:13]
	v_mov_b64_e32 v[26:27], v[10:11]
	v_mov_b64_e32 v[24:25], v[8:9]
	v_mov_b64_e32 v[22:23], v[6:7]
	v_mov_b64_e32 v[20:21], v[4:5]
	v_mov_b64_e32 v[18:19], v[2:3]
	v_mov_b64_e32 v[16:17], v[0:1]
	s_mov_b32 s61, 0
	s_branch .LBB0_792
	.p2align	6
